# NA attention: rel-pos-bias staging loads issued together with the Q loads (one wait instead of three serialized round trips)
# speedup vs baseline: 1.0112x; 1.0005x over previous
; template <int DK, int QB, bool NA>
; DEVI void attn_item(const AttnArgs& a, unsigned char* smem) {
;     ...
; #pragma unroll
;   for (int qb = 0; qb < QB; ++qb) {
;     const bf16_t* qp = a.Q + (size_t)((wact ? w * QB * 16 : 0) + qb * 16 + l16) * a.ldq + g * 8;
; #pragma unroll
;     for (int ks = 0; ks < KS; ++ks) qf[qb][ks] = *(const bf16x8*)(qp + ks * 32);
;   }
;   float m[QB], l[QB];
;   f32x4 o[4][QB];
; #pragma unroll
;   for (int qb = 0; qb < QB; ++qb) {
;     m[qb] = NA ? -1e30f : 0.f; l[qb] = 0.f;
; #pragma unroll
;     for (int db = 0; db < 4; ++db) o[db][qb] = (f32x4){0.f, 0.f, 0.f, 0.f};
;   }
;   const int r8 = tid >> 3, c8 = (tid & 7) ^ ((tid >> 4) & 7);
;   const bf16_t* Kn = a.K + (size_t)r8 * a.ldk + c8 * 8;
;   const bf16_t* Kr = a.K + (size_t)(tid >> 2) * a.ldk + 64 + (((tid & 3) ^ ((0 - (tid >> 4)) & 3)) * 8);
;   const bf16_t* Vg = a.Vt + (size_t)r8 * a.Lk + c8 * 8;
;   const size_t kstep = (size_t)32 * a.ldk, vstep = (size_t)32 * a.Lk;
;   unsigned char* lds_t = smem + tid * 16;
;     ...
;   asm volatile("s_waitcnt vmcnt(0)" ::: "memory");
;   RAW_BARRIER();
;   ATT_ISSUE(0, 0);
;   if (nt > 1) ATT_ISSUE(1, 1);
; DEVI void attn_na_phase(const Params& p, unsigned char* smem, unsigned* ctr) {
;     ...
;     if (it < NS) { const int sh2 = it / 129; R = it - sh2 * 129; s = 8 + (sh2 >> 4); h = sh2 & 15; rows = 128; }
;     else { const int id = it - NS; const int sh2 = id / 65; R = id - sh2 * 65; s = sh2 >> 4; h = sh2 & 15; rows = 64; }
;     const int kb = seq_base(s), Lr = seq_lr(s), Lk = Lr + 64;
;     for (int i = threadIdx.x; i < 465; i += 256) biasL[i] = p.na_rpb[h * 465 + i] * LOG2E;
;     if (threadIdx.x < 16) biasL[480 + threadIdx.x] = p.na_meta_bias[h * 16 + threadIdx.x] * LOG2E;
;     AttnArgs a;
;     a.Lr = Lr; a.Lk = Lk; a.sc2 = 0.125f * LOG2E;
;     a.K = Hb + H_NAQK + (size_t)kb * 2048 + 1024 + h * 64; a.ldk = 2048;
;     a.Vt = Hb + H_VTN + (size_t)1024 * kb + (size_t)(h * 64) * Lk;
;     a.ldq = 2048;
;     int q0;
;     if (R < rows) { const int rs = min(max(R - 4, 0), rows - 8); a.R = R; a.rs = rs; a.first = rs; a.nreg = 8; a.nq = 64; q0 = kb + R * 64; }
;     else { a.R = 0; a.rs = 0; a.first = 0; a.nreg = 0; a.nq = 16; q0 = kb + Lr; }
;     a.Q = Hb + H_NAQK + (size_t)q0 * 2048 + h * 64;
;     a.O = Ob; a.orow0 = q0; a.ocol0 = h * 64;
;     attn_item<64, 1, true>(a, smem);
.LBB0_920:
	s_and_b32 s44, s8, 15
	s_max_i32 s1, s49, 4
	s_add_i32 s1, s1, -4
	s_add_i32 s2, s40, -8
	s_min_u32 s47, s1, s2
	s_cmp_lt_i32 s49, s40
	s_cselect_b64 s[2:3], -1, 0
	s_and_b64 s[2:3], s[2:3], exec
	s_cselect_b32 s1, s47, 0
	s_lshl_b32 s8, s1, 6
	s_cmp_lt_i32 s49, s40
	s_cselect_b64 s[2:3], -1, 0
	s_and_b64 s[2:3], s[2:3], exec
	s_cselect_b32 s52, s8, s46
	s_lshl_b32 s1, s49, 6
	s_cmp_lt_i32 s49, s40
	s_cselect_b64 s[2:3], -1, 0
	s_and_b64 s[42:43], s[2:3], exec
	s_cselect_b32 s48, 64, 16
	s_cselect_b32 s9, s1, s46
	s_ashr_i32 s1, s0, 31
	s_or_b32 s41, s46, 64
	s_lshl_b64 s[42:43], s[0:1], 12
	s_lshl_b32 s45, s44, 6
	s_waitcnt vmcnt(0)
	v_lshl_add_u64 v[2:3], v[158:159], 0, s[42:43]
	s_lshl_b32 s20, s44, 7
	s_lshl_b64 s[42:43], s[0:1], 11
	s_mul_i32 s1, s41, s45
	v_lshl_add_u64 v[16:17], v[2:3], 0, s[20:21]
	v_lshl_add_u64 v[2:3], v[162:163], 0, s[42:43]
	s_lshl_b32 s42, s1, 1
	s_mov_b32 s43, s21
	v_lshl_add_u64 v[18:19], v[2:3], 0, s[42:43]
	s_add_i32 s42, s0, s9
	v_mov_b32_e32 v14, v177
	s_ashr_i32 s43, s42, 31
	s_lshl_b64 s[0:1], s[42:43], 12
	v_ashrrev_i32_e32 v11, 2, v14
	v_and_b32_e32 v13, -16, v11
	v_lshl_add_u64 v[2:3], v[158:159], 0, s[0:1]
	v_lshrrev_b32_e32 v15, 4, v14
	v_cmp_gt_i32_e64 s[0:1], s48, v13
	v_ashrrev_i32_e32 v20, 3, v14
	v_and_b32_e32 v10, 15, v14
	v_cndmask_b32_e64 v0, 0, v13, s[0:1]
	v_xor_b32_e32 v15, v15, v14
	v_ashrrev_i32_e32 v21, 31, v20
	v_or_b32_e32 v4, v0, v10
	v_lshlrev_b64 v[22:23], 12, v[20:21]
	v_lshlrev_b32_e32 v15, 4, v15
	v_ashrrev_i32_e32 v5, 31, v4
	v_lshl_add_u64 v[16:17], v[16:17], 0, v[22:23]
	v_and_b32_e32 v22, 0x70, v15
	v_mov_b32_e32 v23, v1
	s_mov_b32 s53, s21
	v_lshl_add_u64 v[2:3], v[2:3], 0, s[20:21]
	v_bfe_u32 v12, v14, 4, 2
	v_lshlrev_b64 v[4:5], 12, v[4:5]
	v_lshl_add_u64 v[58:59], v[16:17], 0, v[22:23]
	v_mad_i64_i32 v[16:17], s[58:59], v20, s41, 0
	s_lshl_b64 s[54:55], s[52:53], 12
	v_lshl_add_u64 v[2:3], v[2:3], 0, v[4:5]
	v_lshlrev_b32_e32 v0, 4, v12
	v_lshl_add_u64 v[16:17], v[16:17], 1, v[18:19]
	v_lshlrev_b32_e32 v75, 4, v14
	v_lshl_add_u64 v[2:3], v[2:3], 0, v[0:1]
	v_lshl_add_u64 v[60:61], v[16:17], 0, v[22:23]
	v_lshl_add_u64 v[16:17], v[58:59], 0, s[54:55]
	s_mov_b64 s[28:29], 0x800
	v_readfirstlane_b32 s9, v75
	v_add_u32_e32 v15, 0x1000, v75
	v_readlane_b32 s100, v251, 29
	v_readlane_b32 s101, v251, 30
	v_mov_b32_e32 v26, 0x1d1
	v_mad_u32_u24 v26, s44, v26, v177
	v_lshlrev_b32_e32 v26, 2, v26
	s_nop 1
	global_load_dword v24, v26, s[100:101]
	v_cmp_gt_u32_e32 vcc, 0xd1, v177
	s_and_saveexec_b64 vcc, vcc
	global_load_dword v25, v26, s[100:101] offset:1024
	s_mov_b64 exec, vcc
	v_readlane_b32 s100, v251, 31
	v_readlane_b32 s101, v251, 32
	v_lshl_or_b32 v26, s44, 6, v188
	v_cmp_gt_u32_e32 vcc, 16, v177
	s_and_saveexec_b64 vcc, vcc
	s_cbranch_execz .Lna_skip_meta
	s_nop 1
	global_load_dword v26, v26, s[100:101]
.Lna_skip_meta:
	s_mov_b64 exec, vcc
	global_load_dwordx4 v[6:9], v[2:3], off
	s_nop 0
	global_load_dwordx4 v[2:5], v[2:3], off offset:64
	s_waitcnt vmcnt(0)
	v_mul_f32_e32 v24, 0x3fb8aa3b, v24
	ds_write_b32 v189, v24
	v_cmp_gt_u32_e32 vcc, 0xd1, v177
	s_and_saveexec_b64 vcc, vcc
	v_mul_f32_e32 v25, 0x3fb8aa3b, v25
	ds_write_b32 v189, v25 offset:1024
	s_mov_b64 exec, vcc
	v_cmp_gt_u32_e32 vcc, 16, v177
	s_and_saveexec_b64 vcc, vcc
	v_mul_f32_e32 v26, 0x3fb8aa3b, v26
	ds_write_b32 v188, v26 offset:63360
	s_mov_b64 exec, vcc
	v_lshl_add_u64 v[18:19], v[16:17], 0, s[28:29]
	s_mov_b32 m0, s9
	s_mov_b64 s[28:29], 0x20800
	v_readfirstlane_b32 s9, v15
	v_add_u32_e32 v15, 0x3000, v75
	s_lshl_b64 s[52:53], s[52:53], 1
	s_lshl_b32 s56, s41, 6
	s_waitcnt lgkmcnt(0)
	s_barrier
	global_load_lds_dwordx4 v[18:19], off
	v_lshl_add_u64 v[16:17], v[16:17], 0, s[28:29]
	s_mov_b32 m0, s9
	v_readfirstlane_b32 s9, v15
	s_mov_b32 s57, s21
	v_add_u32_e32 v15, 0x4000, v75
	global_load_lds_dwordx4 v[16:17], off
	v_lshl_add_u64 v[16:17], v[60:61], 0, s[52:53]
	s_mov_b32 m0, s9
	v_lshl_add_u64 v[62:63], v[60:61], 0, s[56:57]
	v_readfirstlane_b32 s9, v15
	global_load_lds_dwordx4 v[16:17], off
	v_lshl_add_u64 v[16:17], v[62:63], 0, s[52:53]
	s_mov_b32 m0, s9
	s_cmp_ge_i32 s49, s40
	global_load_lds_dwordx4 v[16:17], off
	s_cbranch_scc1 .LBB0_927
	s_mov_b32 s9, s21
	s_add_i32 s20, s8, 64
	s_lshl_b64 s[40:41], s[8:9], 1
	v_lshl_add_u64 v[16:17], v[62:63], 0, s[40:41]
	s_mov_b64 s[28:29], 0x80
	v_lshl_add_u64 v[18:19], v[60:61], 0, s[40:41]
	s_lshl_b64 s[40:41], s[20:21], 12
	v_add_u32_e32 v26, 0x5000, v75
	v_lshl_add_u64 v[16:17], v[16:17], 0, s[28:29]
	v_lshl_add_u64 v[18:19], v[18:19], 0, s[28:29]
	v_add_u32_e32 v25, 0x6000, v75
	v_lshl_add_u64 v[20:21], v[58:59], 0, s[40:41]
	s_mov_b64 s[28:29], 0x800
	v_readfirstlane_b32 s9, v26
	v_add_u32_e32 v24, 0x8000, v75
	v_lshl_add_u64 v[22:23], v[20:21], 0, s[28:29]
	s_mov_b64 s[28:29], 0x20800
	s_mov_b32 m0, s9
	v_readfirstlane_b32 s9, v25
	v_add_u32_e32 v15, 0x9000, v75
	v_lshl_add_u64 v[20:21], v[20:21], 0, s[28:29]
	global_load_lds_dwordx4 v[22:23], off
	s_mov_b32 m0, s9
	v_readfirstlane_b32 s9, v24
	global_load_lds_dwordx4 v[20:21], off
	s_mov_b32 m0, s9
	v_readfirstlane_b32 s9, v15
	global_load_lds_dwordx4 v[18:19], off
	s_mov_b32 m0, s9
	s_nop 0
	global_load_lds_dwordx4 v[16:17], off
